# baseline (speedup 1.0000x reference)
.LBB0_274:
	ds_read_b128 v[162:165], v161
	ds_read_b128 v[166:169], v161 offset:1024
	ds_read_b128 v[170:173], v161 offset:2048
	ds_read_b128 v[174:177], v161 offset:3072
	ds_read_b128 v[178:181], v152
	ds_read_b128 v[182:185], v152 offset:1024
	ds_read_b128 v[186:189], v151
	ds_read_b128 v[190:193], v151 offset:1024
	ds_read_b128 v[194:197], v150
	ds_read_b128 v[198:201], v150 offset:1024
	ds_read_b128 v[202:205], v149
	ds_read_b128 v[206:209], v149 offset:1024
	s_waitcnt lgkmcnt(8)
	s_waitcnt vmcnt(10)
	s_barrier
	s_waitcnt lgkmcnt(0)
	s_waitcnt lgkmcnt(0)
	v_mfma_f32_16x16x32_bf16 v[124:127], v[162:165], v[178:181], v[124:127]
	v_mfma_f32_16x16x32_bf16 v[120:123], v[170:173], v[178:181], v[120:123]
	v_mfma_f32_16x16x32_bf16 v[116:119], v[162:165], v[186:189], v[116:119]
	v_mfma_f32_16x16x32_bf16 v[112:115], v[170:173], v[186:189], v[112:115]
	v_mfma_f32_16x16x32_bf16 v[108:111], v[162:165], v[194:197], v[108:111]
	v_mfma_f32_16x16x32_bf16 v[104:107], v[170:173], v[194:197], v[104:107]
	v_mfma_f32_16x16x32_bf16 v[100:103], v[162:165], v[202:205], v[100:103]
	v_mfma_f32_16x16x32_bf16 v[96:99], v[170:173], v[202:205], v[96:99]
	v_mfma_f32_16x16x32_bf16 v[124:127], v[166:169], v[182:185], v[124:127]
	v_mfma_f32_16x16x32_bf16 v[120:123], v[174:177], v[182:185], v[120:123]
	v_mfma_f32_16x16x32_bf16 v[116:119], v[166:169], v[190:193], v[116:119]
	v_mfma_f32_16x16x32_bf16 v[112:115], v[174:177], v[190:193], v[112:115]
	v_mfma_f32_16x16x32_bf16 v[108:111], v[166:169], v[198:201], v[108:111]
	v_mfma_f32_16x16x32_bf16 v[104:107], v[174:177], v[198:201], v[104:107]
	v_mfma_f32_16x16x32_bf16 v[100:103], v[166:169], v[206:209], v[100:103]
	v_mfma_f32_16x16x32_bf16 v[96:99], v[174:177], v[206:209], v[96:99]
	s_barrier
	s_mov_b32 vcc_lo, 0xfffbd000
	s_mov_b32 vcc_hi, -1
	s_add_i32 s67, s98, 0x10000
	v_lshl_add_u64 v[226:227], v[130:131], 0, vcc
	s_mov_b32 m0, s67
	s_add_i32 s67, s98, 0x12000
	ds_read_b128 v[210:213], v158
	ds_read_b128 v[214:217], v158 offset:1024
	ds_read_b128 v[218:221], v158 offset:2048
	ds_read_b128 v[222:225], v158 offset:3072
	global_load_lds_dwordx4 v[226:227], off
	v_lshl_add_u64 v[226:227], v[130:131], 0, s[22:23]
	s_mov_b32 m0, s67
	s_add_i32 s66, s66, 2
	global_load_lds_dwordx4 v[226:227], off
	s_mov_b32 s67, s98
	v_lshl_add_u64 v[226:227], v[132:133], 0, s[24:25]
	s_mov_b32 m0, s67
	s_add_i32 s67, s98, 0x2000
	global_load_lds_dwordx4 v[226:227], off nt
	v_lshl_add_u64 v[226:227], v[132:133], 0, s[26:27]
	s_mov_b32 m0, s67
	s_nop 0
	global_load_lds_dwordx4 v[226:227], off nt
	s_waitcnt vmcnt(12)
	s_barrier
	s_waitcnt lgkmcnt(0)
	s_waitcnt lgkmcnt(0)
	v_mfma_f32_16x16x32_bf16 v[92:95], v[210:213], v[178:181], v[92:95]
	v_mfma_f32_16x16x32_bf16 v[88:91], v[218:221], v[178:181], v[88:91]
	v_mfma_f32_16x16x32_bf16 v[84:87], v[210:213], v[186:189], v[84:87]
	v_mfma_f32_16x16x32_bf16 v[80:83], v[218:221], v[186:189], v[80:83]
	v_mfma_f32_16x16x32_bf16 v[76:79], v[210:213], v[194:197], v[76:79]
	v_mfma_f32_16x16x32_bf16 v[72:75], v[218:221], v[194:197], v[72:75]
	v_mfma_f32_16x16x32_bf16 v[68:71], v[210:213], v[202:205], v[68:71]
	v_mfma_f32_16x16x32_bf16 v[64:67], v[218:221], v[202:205], v[64:67]
	v_mfma_f32_16x16x32_bf16 v[92:95], v[214:217], v[182:185], v[92:95]
	v_mfma_f32_16x16x32_bf16 v[88:91], v[222:225], v[182:185], v[88:91]
	v_mfma_f32_16x16x32_bf16 v[84:87], v[214:217], v[190:193], v[84:87]
	v_mfma_f32_16x16x32_bf16 v[80:83], v[222:225], v[190:193], v[80:83]
	v_mfma_f32_16x16x32_bf16 v[76:79], v[214:217], v[198:201], v[76:79]
	v_mfma_f32_16x16x32_bf16 v[72:75], v[222:225], v[198:201], v[72:75]
	v_mfma_f32_16x16x32_bf16 v[68:71], v[214:217], v[206:209], v[68:71]
	v_mfma_f32_16x16x32_bf16 v[64:67], v[222:225], v[206:209], v[64:67]
	s_barrier
	ds_read_b128 v[178:181], v152 offset:16384
	ds_read_b128 v[182:185], v152 offset:17408
	ds_read_b128 v[186:189], v151 offset:16384
	ds_read_b128 v[190:193], v151 offset:17408
	ds_read_b128 v[194:197], v150 offset:16384
	ds_read_b128 v[198:201], v150 offset:17408
	ds_read_b128 v[202:205], v149 offset:16384
	ds_read_b128 v[206:209], v149 offset:17408
	s_add_i32 s67, s98, 0x14000
	v_lshl_add_u64 v[226:227], v[130:131], 0, s[28:29]
	s_mov_b32 m0, s67
	s_add_i32 s67, s98, 0x16000
	global_load_lds_dwordx4 v[226:227], off
	v_lshl_add_u64 v[226:227], v[130:131], 0, s[30:31]
	s_mov_b32 m0, s67
	s_nop 0
	global_load_lds_dwordx4 v[226:227], off
	s_barrier
	s_waitcnt lgkmcnt(0)
	s_waitcnt lgkmcnt(0)
	v_mfma_f32_16x16x32_bf16 v[60:63], v[162:165], v[178:181], v[60:63]
	v_mfma_f32_16x16x32_bf16 v[56:59], v[170:173], v[178:181], v[56:59]
	v_mfma_f32_16x16x32_bf16 v[52:55], v[162:165], v[186:189], v[52:55]
	v_mfma_f32_16x16x32_bf16 v[48:51], v[170:173], v[186:189], v[48:51]
	v_mfma_f32_16x16x32_bf16 v[44:47], v[162:165], v[194:197], v[44:47]
	v_mfma_f32_16x16x32_bf16 v[40:43], v[170:173], v[194:197], v[40:43]
	v_mfma_f32_16x16x32_bf16 v[36:39], v[162:165], v[202:205], v[36:39]
	v_mfma_f32_16x16x32_bf16 v[32:35], v[170:173], v[202:205], v[32:35]
	v_mfma_f32_16x16x32_bf16 v[60:63], v[166:169], v[182:185], v[60:63]
	v_mfma_f32_16x16x32_bf16 v[56:59], v[174:177], v[182:185], v[56:59]
	v_mfma_f32_16x16x32_bf16 v[52:55], v[166:169], v[190:193], v[52:55]
	v_mfma_f32_16x16x32_bf16 v[48:51], v[174:177], v[190:193], v[48:51]
	v_mfma_f32_16x16x32_bf16 v[44:47], v[166:169], v[198:201], v[44:47]
	v_mfma_f32_16x16x32_bf16 v[40:43], v[174:177], v[198:201], v[40:43]
	v_mfma_f32_16x16x32_bf16 v[36:39], v[166:169], v[206:209], v[36:39]
	v_mfma_f32_16x16x32_bf16 v[32:35], v[174:177], v[206:209], v[32:35]
	s_barrier
	s_add_i32 s67, s98, 0x4000
	v_lshl_add_u64 v[164:165], v[132:133], 0, s[34:35]
	s_mov_b32 m0, s67
	s_add_i32 s67, s98, 0x6000
	global_load_lds_dwordx4 v[164:165], off nt
	v_lshl_add_u64 v[164:165], v[132:133], 0, s[44:45]
	s_mov_b32 m0, s67
	s_nop 0
	global_load_lds_dwordx4 v[164:165], off nt
	s_waitcnt vmcnt(12)
	s_barrier
	v_mfma_f32_16x16x32_bf16 v[28:31], v[210:213], v[178:181], v[28:31]
	v_mfma_f32_16x16x32_bf16 v[24:27], v[218:221], v[178:181], v[24:27]
	v_mfma_f32_16x16x32_bf16 v[20:23], v[210:213], v[186:189], v[20:23]
	v_mfma_f32_16x16x32_bf16 v[16:19], v[218:221], v[186:189], v[16:19]
	v_mfma_f32_16x16x32_bf16 v[12:15], v[210:213], v[194:197], v[12:15]
	v_mfma_f32_16x16x32_bf16 v[8:11], v[218:221], v[194:197], v[8:11]
	v_mfma_f32_16x16x32_bf16 v[4:7], v[210:213], v[202:205], v[4:7]
	v_mfma_f32_16x16x32_bf16 v[0:3], v[218:221], v[202:205], v[0:3]
	v_mfma_f32_16x16x32_bf16 v[28:31], v[214:217], v[182:185], v[28:31]
	v_mfma_f32_16x16x32_bf16 v[24:27], v[222:225], v[182:185], v[24:27]
	v_mfma_f32_16x16x32_bf16 v[20:23], v[214:217], v[190:193], v[20:23]
	v_mfma_f32_16x16x32_bf16 v[16:19], v[222:225], v[190:193], v[16:19]
	v_mfma_f32_16x16x32_bf16 v[12:15], v[214:217], v[198:201], v[12:15]
	v_mfma_f32_16x16x32_bf16 v[8:11], v[222:225], v[198:201], v[8:11]
	v_mfma_f32_16x16x32_bf16 v[4:7], v[214:217], v[206:209], v[4:7]
	v_mfma_f32_16x16x32_bf16 v[0:3], v[222:225], v[206:209], v[0:3]
	s_barrier
	ds_read_b128 v[162:165], v154
	ds_read_b128 v[166:169], v154 offset:1024
	ds_read_b128 v[170:173], v154 offset:2048
	ds_read_b128 v[174:177], v154 offset:3072
	ds_read_b128 v[178:181], v152 offset:32768
	ds_read_b128 v[182:185], v152 offset:33792
	ds_read_b128 v[186:189], v151 offset:32768
	ds_read_b128 v[190:193], v151 offset:33792
	ds_read_b128 v[194:197], v150 offset:32768
	ds_read_b128 v[198:201], v150 offset:33792
	ds_read_b128 v[202:205], v149 offset:32768
	ds_read_b128 v[206:209], v149 offset:33792
	s_waitcnt lgkmcnt(8)
	s_waitcnt vmcnt(10)
	s_barrier
	s_waitcnt lgkmcnt(0)
	s_waitcnt lgkmcnt(0)
	v_mfma_f32_16x16x32_bf16 v[124:127], v[162:165], v[178:181], v[124:127]
	v_mfma_f32_16x16x32_bf16 v[120:123], v[170:173], v[178:181], v[120:123]
	v_mfma_f32_16x16x32_bf16 v[116:119], v[162:165], v[186:189], v[116:119]
	v_mfma_f32_16x16x32_bf16 v[112:115], v[170:173], v[186:189], v[112:115]
	v_mfma_f32_16x16x32_bf16 v[108:111], v[162:165], v[194:197], v[108:111]
	v_mfma_f32_16x16x32_bf16 v[104:107], v[170:173], v[194:197], v[104:107]
	v_mfma_f32_16x16x32_bf16 v[100:103], v[162:165], v[202:205], v[100:103]
	v_mfma_f32_16x16x32_bf16 v[96:99], v[170:173], v[202:205], v[96:99]
	v_mfma_f32_16x16x32_bf16 v[124:127], v[166:169], v[182:185], v[124:127]
	v_mfma_f32_16x16x32_bf16 v[120:123], v[174:177], v[182:185], v[120:123]
	v_mfma_f32_16x16x32_bf16 v[116:119], v[166:169], v[190:193], v[116:119]
	v_mfma_f32_16x16x32_bf16 v[112:115], v[174:177], v[190:193], v[112:115]
	v_mfma_f32_16x16x32_bf16 v[108:111], v[166:169], v[198:201], v[108:111]
	v_mfma_f32_16x16x32_bf16 v[104:107], v[174:177], v[198:201], v[104:107]
	v_mfma_f32_16x16x32_bf16 v[100:103], v[166:169], v[206:209], v[100:103]
	v_mfma_f32_16x16x32_bf16 v[96:99], v[174:177], v[206:209], v[96:99]
	s_barrier
	s_add_i32 s67, s98, 0x18000
	v_lshl_add_u64 v[226:227], v[130:131], 0, s[46:47]
	s_mov_b32 m0, s67
	s_add_i32 s67, s98, 0x1a000
	ds_read_b128 v[210:213], v153
	ds_read_b128 v[214:217], v153 offset:1024
	ds_read_b128 v[218:221], v153 offset:2048
	ds_read_b128 v[222:225], v153 offset:3072
	global_load_lds_dwordx4 v[226:227], off
	v_lshl_add_u64 v[226:227], v[130:131], 0, s[56:57]
	s_mov_b32 m0, s67
	s_nop 0
	global_load_lds_dwordx4 v[226:227], off
	s_add_i32 s67, s98, 0x8000
	v_lshl_add_u64 v[226:227], v[132:133], 0, s[58:59]
	s_mov_b32 m0, s67
	s_add_i32 s67, s98, 0xa000
	global_load_lds_dwordx4 v[226:227], off nt
	s_mov_b32 m0, s67
	s_nop 0
	global_load_lds_dwordx4 v[132:133], off nt
	s_waitcnt vmcnt(12)
	s_barrier
	s_waitcnt lgkmcnt(0)
	s_waitcnt lgkmcnt(0)
	v_mfma_f32_16x16x32_bf16 v[92:95], v[210:213], v[178:181], v[92:95]
	v_mfma_f32_16x16x32_bf16 v[88:91], v[218:221], v[178:181], v[88:91]
	v_mfma_f32_16x16x32_bf16 v[84:87], v[210:213], v[186:189], v[84:87]
	v_mfma_f32_16x16x32_bf16 v[80:83], v[218:221], v[186:189], v[80:83]
	v_mfma_f32_16x16x32_bf16 v[76:79], v[210:213], v[194:197], v[76:79]
	v_mfma_f32_16x16x32_bf16 v[72:75], v[218:221], v[194:197], v[72:75]
	v_mfma_f32_16x16x32_bf16 v[68:71], v[210:213], v[202:205], v[68:71]
	v_mfma_f32_16x16x32_bf16 v[64:67], v[218:221], v[202:205], v[64:67]
	v_mfma_f32_16x16x32_bf16 v[92:95], v[214:217], v[182:185], v[92:95]
	v_mfma_f32_16x16x32_bf16 v[88:91], v[222:225], v[182:185], v[88:91]
	v_mfma_f32_16x16x32_bf16 v[84:87], v[214:217], v[190:193], v[84:87]
	v_mfma_f32_16x16x32_bf16 v[80:83], v[222:225], v[190:193], v[80:83]
	v_mfma_f32_16x16x32_bf16 v[76:79], v[214:217], v[198:201], v[76:79]
	v_mfma_f32_16x16x32_bf16 v[72:75], v[222:225], v[198:201], v[72:75]
	v_mfma_f32_16x16x32_bf16 v[68:71], v[214:217], v[206:209], v[68:71]
	v_mfma_f32_16x16x32_bf16 v[64:67], v[222:225], v[206:209], v[64:67]
	s_barrier
	ds_read_b128 v[178:181], v152 offset:49152
	ds_read_b128 v[182:185], v152 offset:50176
	ds_read_b128 v[186:189], v151 offset:49152
	ds_read_b128 v[190:193], v151 offset:50176
	ds_read_b128 v[194:197], v150 offset:49152
	ds_read_b128 v[198:201], v150 offset:50176
	ds_read_b128 v[202:205], v149 offset:49152
	ds_read_b128 v[206:209], v149 offset:50176
	s_add_i32 s67, s98, 0x1c000
	v_lshl_add_u64 v[226:227], v[130:131], 0, s[58:59]
	s_mov_b32 m0, s67
	s_add_i32 s67, s98, 0x1e000
	global_load_lds_dwordx4 v[226:227], off
	s_mov_b32 m0, s67
	s_nop 0
	global_load_lds_dwordx4 v[130:131], off
	s_barrier
	s_waitcnt lgkmcnt(0)
	s_waitcnt lgkmcnt(0)
	v_mfma_f32_16x16x32_bf16 v[60:63], v[162:165], v[178:181], v[60:63]
	v_mfma_f32_16x16x32_bf16 v[56:59], v[170:173], v[178:181], v[56:59]
	v_mfma_f32_16x16x32_bf16 v[52:55], v[162:165], v[186:189], v[52:55]
	v_mfma_f32_16x16x32_bf16 v[48:51], v[170:173], v[186:189], v[48:51]
	v_mfma_f32_16x16x32_bf16 v[44:47], v[162:165], v[194:197], v[44:47]
	v_mfma_f32_16x16x32_bf16 v[40:43], v[170:173], v[194:197], v[40:43]
	v_mfma_f32_16x16x32_bf16 v[36:39], v[162:165], v[202:205], v[36:39]
	v_mfma_f32_16x16x32_bf16 v[32:35], v[170:173], v[202:205], v[32:35]
	v_mfma_f32_16x16x32_bf16 v[60:63], v[166:169], v[182:185], v[60:63]
	v_mfma_f32_16x16x32_bf16 v[56:59], v[174:177], v[182:185], v[56:59]
	v_mfma_f32_16x16x32_bf16 v[52:55], v[166:169], v[190:193], v[52:55]
	v_mfma_f32_16x16x32_bf16 v[48:51], v[174:177], v[190:193], v[48:51]
	v_mfma_f32_16x16x32_bf16 v[44:47], v[166:169], v[198:201], v[44:47]
	v_mfma_f32_16x16x32_bf16 v[40:43], v[174:177], v[198:201], v[40:43]
	v_mfma_f32_16x16x32_bf16 v[36:39], v[166:169], v[206:209], v[36:39]
	v_mfma_f32_16x16x32_bf16 v[32:35], v[174:177], v[206:209], v[32:35]
	s_barrier
	v_lshl_add_u64 v[132:133], v[132:133], 0, s[62:63]
	s_mov_b32 vcc_lo, 0xffe01000
	s_mov_b32 vcc_hi, -1
	v_lshl_add_u64 v[164:165], v[132:133], 0, vcc
	s_add_i32 s67, s98, 0xc000
	s_mov_b32 vcc_lo, 0xffe02000
	s_mov_b32 m0, s67
	s_mov_b32 vcc_hi, -1
	s_add_i32 s67, s98, 0xe000
	global_load_lds_dwordx4 v[164:165], off nt
	v_lshl_add_u64 v[164:165], v[132:133], 0, vcc
	s_mov_b32 m0, s67
	s_nop 0
	global_load_lds_dwordx4 v[164:165], off nt
	s_waitcnt vmcnt(12)
	s_barrier
	v_mfma_f32_16x16x32_bf16 v[28:31], v[210:213], v[178:181], v[28:31]
	v_mfma_f32_16x16x32_bf16 v[24:27], v[218:221], v[178:181], v[24:27]
	v_mfma_f32_16x16x32_bf16 v[20:23], v[210:213], v[186:189], v[20:23]
	v_mfma_f32_16x16x32_bf16 v[16:19], v[218:221], v[186:189], v[16:19]
	v_mfma_f32_16x16x32_bf16 v[12:15], v[210:213], v[194:197], v[12:15]
	v_mfma_f32_16x16x32_bf16 v[8:11], v[218:221], v[194:197], v[8:11]
	v_mfma_f32_16x16x32_bf16 v[4:7], v[210:213], v[202:205], v[4:7]
	v_mfma_f32_16x16x32_bf16 v[0:3], v[218:221], v[202:205], v[0:3]
	v_mfma_f32_16x16x32_bf16 v[28:31], v[214:217], v[182:185], v[28:31]
	v_mfma_f32_16x16x32_bf16 v[24:27], v[222:225], v[182:185], v[24:27]
	v_mfma_f32_16x16x32_bf16 v[20:23], v[214:217], v[190:193], v[20:23]
	v_mfma_f32_16x16x32_bf16 v[16:19], v[222:225], v[190:193], v[16:19]
	v_mfma_f32_16x16x32_bf16 v[12:15], v[214:217], v[198:201], v[12:15]
	v_mfma_f32_16x16x32_bf16 v[8:11], v[222:225], v[198:201], v[8:11]
	v_mfma_f32_16x16x32_bf16 v[4:7], v[214:217], v[206:209], v[4:7]
	v_mfma_f32_16x16x32_bf16 v[0:3], v[222:225], v[206:209], v[0:3]
	v_lshl_add_u64 v[130:131], v[130:131], 0, s[60:61]
	s_cmp_lt_u32 s66, s65
	s_barrier
	s_cbranch_scc1 .LBB0_274
	s_lshl_b32 s65, s86, 5
	s_lshl_b32 s66, s86, 8
	s_and_b32 s65, s65, 0x1800
	s_and_b32 s66, s66, 0x700
	s_or_b32 s97, s66, s65
	s_lshl_b32 s65, s97, 6
	s_add_u32 s65, s68, s65
	s_addc_u32 s86, s69, 0
	s_add_i32 s20, s20, -1
	s_lshl_b64 s[66:67], s[20:21], 20
	v_add_u32_e32 v128, v156, v157
	s_add_u32 s66, s65, s66
	v_or_b32_e32 v128, v128, v155
	s_addc_u32 s67, s86, s67
	v_lshl_add_u64 v[156:157], s[66:67], 0, v[128:129]
	v_readfirstlane_b32 s20, v160
	v_lshl_add_u64 v[206:207], v[156:157], 0, s[4:5]
	s_mov_b32 m0, s20
	v_readfirstlane_b32 s20, v159
	ds_read_b128 v[130:133], v161
	ds_read_b128 v[162:165], v161 offset:1024
	ds_read_b128 v[166:169], v161 offset:2048
	ds_read_b128 v[170:173], v161 offset:3072
	ds_read_b128 v[174:177], v152
	ds_read_b128 v[178:181], v152 offset:1024
	ds_read_b128 v[182:185], v151
	ds_read_b128 v[186:189], v151 offset:1024
	ds_read_b128 v[190:193], v150
	ds_read_b128 v[194:197], v150 offset:1024
	ds_read_b128 v[198:201], v149
	ds_read_b128 v[202:205], v149 offset:1024
	global_load_lds_dwordx4 v[206:207], off
	v_lshl_add_u64 v[156:157], v[156:157], 0, s[6:7]
	s_mov_b32 m0, s20
	s_nop 0
	global_load_lds_dwordx4 v[156:157], off
	s_waitcnt vmcnt(10)
	s_barrier
	s_waitcnt lgkmcnt(0)
	s_setprio 1
	s_waitcnt lgkmcnt(0)
	v_mfma_f32_16x16x32_bf16 v[124:127], v[130:133], v[174:177], v[124:127]
	v_mfma_f32_16x16x32_bf16 v[120:123], v[166:169], v[174:177], v[120:123]
	v_mfma_f32_16x16x32_bf16 v[116:119], v[130:133], v[182:185], v[116:119]
	v_mfma_f32_16x16x32_bf16 v[112:115], v[166:169], v[182:185], v[112:115]
	v_mfma_f32_16x16x32_bf16 v[108:111], v[130:133], v[190:193], v[108:111]
	v_mfma_f32_16x16x32_bf16 v[104:107], v[166:169], v[190:193], v[104:107]
	v_mfma_f32_16x16x32_bf16 v[100:103], v[130:133], v[198:201], v[100:103]
	v_mfma_f32_16x16x32_bf16 v[96:99], v[166:169], v[198:201], v[96:99]
	v_mfma_f32_16x16x32_bf16 v[124:127], v[162:165], v[178:181], v[124:127]
	v_mfma_f32_16x16x32_bf16 v[120:123], v[170:173], v[178:181], v[120:123]
	v_mfma_f32_16x16x32_bf16 v[116:119], v[162:165], v[186:189], v[116:119]
	v_mfma_f32_16x16x32_bf16 v[112:115], v[170:173], v[186:189], v[112:115]
	v_mfma_f32_16x16x32_bf16 v[108:111], v[162:165], v[194:197], v[108:111]
	v_mfma_f32_16x16x32_bf16 v[104:107], v[170:173], v[194:197], v[104:107]
	v_mfma_f32_16x16x32_bf16 v[100:103], v[162:165], v[202:205], v[100:103]
	v_mfma_f32_16x16x32_bf16 v[96:99], v[170:173], v[202:205], v[96:99]
	s_setprio 0
	s_barrier
	ds_read_b128 v[206:209], v158
	ds_read_b128 v[210:213], v158 offset:1024
	ds_read_b128 v[214:217], v158 offset:2048
	ds_read_b128 v[156:159], v158 offset:3072
	s_barrier
	s_waitcnt lgkmcnt(0)
	s_setprio 1
	s_waitcnt lgkmcnt(0)
	v_mfma_f32_16x16x32_bf16 v[92:95], v[206:209], v[174:177], v[92:95]
	v_mfma_f32_16x16x32_bf16 v[88:91], v[214:217], v[174:177], v[88:91]
	v_mfma_f32_16x16x32_bf16 v[84:87], v[206:209], v[182:185], v[84:87]
	v_mfma_f32_16x16x32_bf16 v[80:83], v[214:217], v[182:185], v[80:83]
	v_mfma_f32_16x16x32_bf16 v[76:79], v[206:209], v[190:193], v[76:79]
	v_mfma_f32_16x16x32_bf16 v[72:75], v[214:217], v[190:193], v[72:75]
	v_mfma_f32_16x16x32_bf16 v[68:71], v[206:209], v[198:201], v[68:71]
	v_mfma_f32_16x16x32_bf16 v[64:67], v[214:217], v[198:201], v[64:67]
	v_mfma_f32_16x16x32_bf16 v[174:177], v[210:213], v[178:181], v[92:95]
	v_mfma_f32_16x16x32_bf16 v[178:181], v[156:159], v[178:181], v[88:91]
	v_mfma_f32_16x16x32_bf16 v[182:185], v[210:213], v[186:189], v[84:87]
	v_mfma_f32_16x16x32_bf16 v[186:189], v[156:159], v[186:189], v[80:83]
	v_mfma_f32_16x16x32_bf16 v[190:193], v[210:213], v[194:197], v[76:79]
	v_mfma_f32_16x16x32_bf16 v[194:197], v[156:159], v[194:197], v[72:75]
	v_mfma_f32_16x16x32_bf16 v[198:201], v[210:213], v[202:205], v[68:71]
	v_mfma_f32_16x16x32_bf16 v[202:205], v[156:159], v[202:205], v[64:67]
	s_setprio 0
	s_barrier
	s_nop 0
	ds_read_b128 v[64:67], v152 offset:16384
	ds_read_b128 v[68:71], v152 offset:17408
	ds_read_b128 v[72:75], v151 offset:16384
	ds_read_b128 v[76:79], v151 offset:17408
	ds_read_b128 v[80:83], v150 offset:16384
	ds_read_b128 v[84:87], v150 offset:17408
	ds_read_b128 v[88:91], v149 offset:16384
	ds_read_b128 v[92:95], v149 offset:17408
	s_waitcnt vmcnt(4)
	s_barrier
	s_waitcnt lgkmcnt(0)
	s_setprio 1
	s_waitcnt lgkmcnt(0)
	v_mfma_f32_16x16x32_bf16 v[60:63], v[130:133], v[64:67], v[60:63]
	v_mfma_f32_16x16x32_bf16 v[56:59], v[166:169], v[64:67], v[56:59]
	v_mfma_f32_16x16x32_bf16 v[52:55], v[130:133], v[72:75], v[52:55]
	v_mfma_f32_16x16x32_bf16 v[48:51], v[166:169], v[72:75], v[48:51]
	v_mfma_f32_16x16x32_bf16 v[218:221], v[130:133], v[80:83], v[44:47]
	v_mfma_f32_16x16x32_bf16 v[222:225], v[166:169], v[80:83], v[40:43]
	v_mfma_f32_16x16x32_bf16 v[130:133], v[130:133], v[88:91], v[36:39]
	v_mfma_f32_16x16x32_bf16 v[166:169], v[166:169], v[88:91], v[32:35]
	v_mfma_f32_16x16x32_bf16 v[32:35], v[162:165], v[68:71], v[60:63]
	v_mfma_f32_16x16x32_bf16 v[36:39], v[170:173], v[68:71], v[56:59]
	v_mfma_f32_16x16x32_bf16 v[40:43], v[162:165], v[76:79], v[52:55]
	v_mfma_f32_16x16x32_bf16 v[44:47], v[170:173], v[76:79], v[48:51]
	v_mfma_f32_16x16x32_bf16 v[48:51], v[162:165], v[84:87], v[218:221]
	v_mfma_f32_16x16x32_bf16 v[52:55], v[170:173], v[84:87], v[222:225]
	v_mfma_f32_16x16x32_bf16 v[56:59], v[162:165], v[92:95], v[130:133]
	v_mfma_f32_16x16x32_bf16 v[60:63], v[170:173], v[92:95], v[166:169]
	s_setprio 0
	s_setprio 1
	v_mfma_f32_16x16x32_bf16 v[28:31], v[206:209], v[64:67], v[28:31]
	v_mfma_f32_16x16x32_bf16 v[24:27], v[214:217], v[64:67], v[24:27]
	v_mfma_f32_16x16x32_bf16 v[20:23], v[206:209], v[72:75], v[20:23]
	v_mfma_f32_16x16x32_bf16 v[64:67], v[214:217], v[72:75], v[16:19]
	v_mfma_f32_16x16x32_bf16 v[72:75], v[206:209], v[80:83], v[12:15]
	v_mfma_f32_16x16x32_bf16 v[8:11], v[214:217], v[80:83], v[8:11]
	v_mfma_f32_16x16x32_bf16 v[80:83], v[206:209], v[88:91], v[4:7]
	v_mfma_f32_16x16x32_bf16 v[0:3], v[214:217], v[88:91], v[0:3]
	v_mfma_f32_16x16x32_bf16 v[4:7], v[210:213], v[68:71], v[28:31]
	v_mfma_f32_16x16x32_bf16 v[12:15], v[156:159], v[68:71], v[24:27]
	v_mfma_f32_16x16x32_bf16 v[16:19], v[210:213], v[76:79], v[20:23]
	v_mfma_f32_16x16x32_bf16 v[20:23], v[156:159], v[76:79], v[64:67]
	v_mfma_f32_16x16x32_bf16 v[24:27], v[210:213], v[84:87], v[72:75]
	v_mfma_f32_16x16x32_bf16 v[28:31], v[156:159], v[84:87], v[8:11]
	v_mfma_f32_16x16x32_bf16 v[64:67], v[210:213], v[92:95], v[80:83]
	v_mfma_f32_16x16x32_bf16 v[68:71], v[156:159], v[92:95], v[0:3]
	s_setprio 0
	s_barrier
	ds_read_b128 v[8:11], v154
	ds_read_b128 v[0:3], v154 offset:1024
	ds_read_b128 v[76:79], v154 offset:2048
	ds_read_b128 v[72:75], v154 offset:3072
	ds_read_b128 v[130:133], v152 offset:32768
	ds_read_b128 v[154:157], v152 offset:33792
	ds_read_b128 v[158:161], v151 offset:32768
	ds_read_b128 v[162:165], v151 offset:33792
	ds_read_b128 v[166:169], v150 offset:32768
	ds_read_b128 v[170:173], v150 offset:33792
	ds_read_b128 v[206:209], v149 offset:32768
	ds_read_b128 v[210:213], v149 offset:33792
	s_waitcnt vmcnt(2)
	s_barrier
	s_waitcnt lgkmcnt(0)
	s_setprio 1
	s_waitcnt lgkmcnt(0)
	v_mfma_f32_16x16x32_bf16 v[80:83], v[8:11], v[130:133], v[124:127]
	v_mfma_f32_16x16x32_bf16 v[84:87], v[76:79], v[130:133], v[120:123]
	v_mfma_f32_16x16x32_bf16 v[88:91], v[8:11], v[158:161], v[116:119]
	v_mfma_f32_16x16x32_bf16 v[92:95], v[76:79], v[158:161], v[112:115]
	v_mfma_f32_16x16x32_bf16 v[108:111], v[8:11], v[166:169], v[108:111]
	v_mfma_f32_16x16x32_bf16 v[104:107], v[76:79], v[166:169], v[104:107]
	v_mfma_f32_16x16x32_bf16 v[100:103], v[8:11], v[206:209], v[100:103]
	v_mfma_f32_16x16x32_bf16 v[96:99], v[76:79], v[206:209], v[96:99]
	v_mfma_f32_16x16x32_bf16 v[112:115], v[0:3], v[154:157], v[80:83]
	v_mfma_f32_16x16x32_bf16 v[116:119], v[72:75], v[154:157], v[84:87]
	v_mfma_f32_16x16x32_bf16 v[120:123], v[0:3], v[162:165], v[88:91]
	v_mfma_f32_16x16x32_bf16 v[124:127], v[72:75], v[162:165], v[92:95]
	v_mfma_f32_16x16x32_bf16 v[108:111], v[0:3], v[170:173], v[108:111]
	v_mfma_f32_16x16x32_bf16 v[104:107], v[72:75], v[170:173], v[104:107]
	v_mfma_f32_16x16x32_bf16 v[100:103], v[0:3], v[210:213], v[100:103]
	v_mfma_f32_16x16x32_bf16 v[96:99], v[72:75], v[210:213], v[96:99]
	s_setprio 0
	s_barrier
	ds_read_b128 v[88:91], v153
	ds_read_b128 v[80:83], v153 offset:1024
	ds_read_b128 v[92:95], v153 offset:2048
	ds_read_b128 v[84:87], v153 offset:3072
	s_waitcnt vmcnt(0)
	s_barrier
	s_waitcnt lgkmcnt(0)
	s_setprio 1
	s_waitcnt lgkmcnt(0)
	v_mfma_f32_16x16x32_bf16 v[174:177], v[88:91], v[130:133], v[174:177]
	v_mfma_f32_16x16x32_bf16 v[130:133], v[92:95], v[130:133], v[178:181]
	v_mfma_f32_16x16x32_bf16 v[178:181], v[88:91], v[158:161], v[182:185]
	v_mfma_f32_16x16x32_bf16 v[158:161], v[92:95], v[158:161], v[186:189]
	v_mfma_f32_16x16x32_bf16 v[182:185], v[88:91], v[166:169], v[190:193]
	v_mfma_f32_16x16x32_bf16 v[166:169], v[92:95], v[166:169], v[194:197]
	v_mfma_f32_16x16x32_bf16 v[186:189], v[88:91], v[206:209], v[198:201]
	v_mfma_f32_16x16x32_bf16 v[190:193], v[92:95], v[206:209], v[202:205]
	v_mfma_f32_16x16x32_bf16 v[174:177], v[80:83], v[154:157], v[174:177]
	v_mfma_f32_16x16x32_bf16 v[130:133], v[84:87], v[154:157], v[130:133]
	v_mfma_f32_16x16x32_bf16 v[154:157], v[80:83], v[162:165], v[178:181]
	v_mfma_f32_16x16x32_bf16 v[158:161], v[84:87], v[162:165], v[158:161]
	v_mfma_f32_16x16x32_bf16 v[162:165], v[80:83], v[170:173], v[182:185]
	v_mfma_f32_16x16x32_bf16 v[166:169], v[84:87], v[170:173], v[166:169]
	v_mfma_f32_16x16x32_bf16 v[170:173], v[80:83], v[210:213], v[186:189]
	v_mfma_f32_16x16x32_bf16 v[178:181], v[84:87], v[210:213], v[190:193]
	s_setprio 0
	s_barrier
	v_mbcnt_lo_u32_b32 v128, -1, 0
	v_mbcnt_hi_u32_b32 v128, -1, v128
	v_cvt_pk_bf16_f32 v112, v112, v113
	v_cvt_pk_bf16_f32 v113, v114, v115
	v_cvt_pk_bf16_f32 v114, v116, v117
	v_cvt_pk_bf16_f32 v115, v118, v119
	s_lshl_b32 s89, s64, 9
	v_add_u32_e32 v153, s72, v128
	v_ashrrev_i32_e32 v182, 6, v153
	v_and_b32_e32 v183, 15, v128
	v_and_b32_e32 v184, 48, v128
	v_mul_lo_u32 v185, v182, s77
	v_bfe_u32 v186, v128, 3, 3
	v_lshlrev_b32_e32 v128, 4, v128
	v_add_u32_e32 v185, 0x20000, v185
	v_lshrrev_b32_e32 v153, 2, v153
	v_and_b32_e32 v128, 0x70, v128
	v_mul_u32_u24_e32 v183, 0x90, v183
	v_and_b32_e32 v153, 64, v153
	v_add3_u32 v183, v185, v183, v184
	v_or_b32_e32 v184, v185, v128
	v_or3_b32 v153, s97, v153, v186
	v_mad_u32_u24 v184, v186, s79, v184
	ds_write_b128 v183, v[112:115]
	v_cvt_pk_bf16_f32 v112, v174, v175
	v_cvt_pk_bf16_f32 v113, v176, v177
	v_cvt_pk_bf16_f32 v114, v130, v131
	v_cvt_pk_bf16_f32 v115, v132, v133
	ds_write_b128 v183, v[112:115] offset:64
	v_lshlrev_b32_e32 v182, 7, v182
	ds_read_b128 v[112:115], v184
	v_lshlrev_b32_e32 v116, 12, v153
	v_and_or_b32 v116, v182, s80, v116
	v_or3_b32 v128, v116, s89, v128
	ds_read_b128 v[116:119], v184 offset:1152
	v_lshl_add_u64 v[130:131], s[0:1], 0, v[128:129]
	s_mov_b32 s20, 0x8000
	s_waitcnt lgkmcnt(0)
	global_store_dwordx4 v128, v[112:115], s[0:1]
	v_cvt_pk_bf16_f32 v108, v108, v109
	v_cvt_pk_bf16_f32 v109, v110, v111
	v_cvt_pk_bf16_f32 v110, v104, v105
	v_cvt_pk_bf16_f32 v111, v106, v107
	v_cvt_pk_bf16_f32 v104, v162, v163
	s_nop 1
	v_add_co_u32_e32 v112, vcc, s20, v130
	v_cvt_pk_bf16_f32 v114, v124, v125
	v_cvt_pk_bf16_f32 v115, v126, v127
	v_cvt_pk_bf16_f32 v105, v164, v165
	v_cvt_pk_bf16_f32 v106, v166, v167
	s_nop 1
	v_addc_co_u32_e32 v113, vcc, 0, v131, vcc
	global_store_dwordx4 v[112:113], v[116:119], off
	v_cvt_pk_bf16_f32 v112, v120, v121
	v_cvt_pk_bf16_f32 v113, v122, v123
	ds_write_b128 v183, v[112:115]
	v_cvt_pk_bf16_f32 v112, v154, v155
	v_cvt_pk_bf16_f32 v113, v156, v157
	v_cvt_pk_bf16_f32 v114, v158, v159
	v_cvt_pk_bf16_f32 v115, v160, v161
	ds_write_b128 v183, v[112:115] offset:64
	ds_read_b128 v[112:115], v184
	ds_read_b128 v[116:119], v184 offset:1152
	v_add_co_u32_e32 v120, vcc, s74, v130
	ds_write_b128 v183, v[108:111]
	v_cvt_pk_bf16_f32 v107, v168, v169
	ds_write_b128 v183, v[104:107] offset:64
	v_addc_co_u32_e32 v121, vcc, 0, v131, vcc
	ds_read_b128 v[104:107], v184
	ds_read_b128 v[108:111], v184 offset:1152
	s_waitcnt lgkmcnt(0)
	global_store_dwordx4 v[120:121], v[112:115], off
	v_cvt_pk_bf16_f32 v100, v100, v101
	v_cvt_pk_bf16_f32 v101, v102, v103
	v_cvt_pk_bf16_f32 v102, v96, v97
	v_cvt_pk_bf16_f32 v103, v98, v99
	ds_write_b128 v183, v[100:103]
	s_nop 0
	v_add_co_u32_e32 v112, vcc, s75, v130
	v_cvt_pk_bf16_f32 v96, v170, v171
	v_cvt_pk_bf16_f32 v97, v172, v173
	v_cvt_pk_bf16_f32 v98, v178, v179
	v_cvt_pk_bf16_f32 v99, v180, v181
	s_nop 1
	v_addc_co_u32_e32 v113, vcc, 0, v131, vcc
	global_store_dwordx4 v[112:113], v[116:119], off
	v_add_co_u32_e32 v112, vcc, s78, v130
	ds_write_b128 v183, v[96:99] offset:64
	s_nop 0
	v_addc_co_u32_e32 v113, vcc, 0, v131, vcc
	ds_read_b128 v[96:99], v184
	ds_read_b128 v[100:103], v184 offset:1152
	global_store_dwordx4 v[112:113], v[104:107], off
	s_nop 1
	v_add_co_u32_e32 v104, vcc, s81, v130
	s_nop 1
	v_addc_co_u32_e32 v105, vcc, 0, v131, vcc
	global_store_dwordx4 v[104:105], v[108:111], off
	v_add_co_u32_e32 v104, vcc, s82, v130
	s_nop 1
	v_addc_co_u32_e32 v105, vcc, 0, v131, vcc
	s_waitcnt lgkmcnt(0)
	global_store_dwordx4 v[104:105], v[96:99], off
	s_nop 1
	v_add_co_u32_e32 v96, vcc, s83, v130
	s_nop 1
	v_addc_co_u32_e32 v97, vcc, 0, v131, vcc
	global_store_dwordx4 v[96:97], v[100:103], off
	ds_read_b128 v[96:99], v152 offset:49152
	ds_read_b128 v[100:103], v152 offset:50176
	ds_read_b128 v[104:107], v151 offset:49152
	ds_read_b128 v[108:111], v151 offset:50176
	ds_read_b128 v[112:115], v150 offset:49152
	ds_read_b128 v[116:119], v150 offset:50176
	ds_read_b128 v[120:123], v149 offset:49152
	ds_read_b128 v[124:127], v149 offset:50176
	s_barrier
	s_waitcnt lgkmcnt(0)
	s_setprio 1
	s_waitcnt lgkmcnt(0)
	v_mfma_f32_16x16x32_bf16 v[32:35], v[8:11], v[96:99], v[32:35]
	v_mfma_f32_16x16x32_bf16 v[36:39], v[76:79], v[96:99], v[36:39]
	v_mfma_f32_16x16x32_bf16 v[40:43], v[8:11], v[104:107], v[40:43]
	v_mfma_f32_16x16x32_bf16 v[130:133], v[76:79], v[104:107], v[44:47]
	v_mfma_f32_16x16x32_bf16 v[150:153], v[8:11], v[112:115], v[48:51]
	v_mfma_f32_16x16x32_bf16 v[52:55], v[76:79], v[112:115], v[52:55]
	v_mfma_f32_16x16x32_bf16 v[8:11], v[8:11], v[120:123], v[56:59]
	v_mfma_f32_16x16x32_bf16 v[60:63], v[76:79], v[120:123], v[60:63]
	v_mfma_f32_16x16x32_bf16 v[56:59], v[0:3], v[100:103], v[32:35]
	v_mfma_f32_16x16x32_bf16 v[48:51], v[72:75], v[100:103], v[36:39]
	v_mfma_f32_16x16x32_bf16 v[44:47], v[0:3], v[108:111], v[40:43]
	v_mfma_f32_16x16x32_bf16 v[40:43], v[72:75], v[108:111], v[130:133]
	v_mfma_f32_16x16x32_bf16 v[36:39], v[0:3], v[116:119], v[150:153]
	v_mfma_f32_16x16x32_bf16 v[32:35], v[72:75], v[116:119], v[52:55]
	v_mfma_f32_16x16x32_bf16 v[8:11], v[0:3], v[124:127], v[8:11]
	v_mfma_f32_16x16x32_bf16 v[0:3], v[72:75], v[124:127], v[60:63]
	s_setprio 0
	s_setprio 1
	v_mfma_f32_16x16x32_bf16 v[4:7], v[88:91], v[96:99], v[4:7]
	v_mfma_f32_16x16x32_bf16 v[12:15], v[92:95], v[96:99], v[12:15]
	v_mfma_f32_16x16x32_bf16 v[16:19], v[88:91], v[104:107], v[16:19]
	v_mfma_f32_16x16x32_bf16 v[20:23], v[92:95], v[104:107], v[20:23]
	v_mfma_f32_16x16x32_bf16 v[72:75], v[88:91], v[112:115], v[24:27]
	v_mfma_f32_16x16x32_bf16 v[76:79], v[92:95], v[112:115], v[28:31]
	v_mfma_f32_16x16x32_bf16 v[64:67], v[88:91], v[120:123], v[64:67]
	v_mfma_f32_16x16x32_bf16 v[68:71], v[92:95], v[120:123], v[68:71]
	v_mfma_f32_16x16x32_bf16 v[60:63], v[80:83], v[100:103], v[4:7]
	v_mfma_f32_16x16x32_bf16 v[52:55], v[84:87], v[100:103], v[12:15]
	v_mfma_f32_16x16x32_bf16 v[28:31], v[80:83], v[108:111], v[16:19]
	v_mfma_f32_16x16x32_bf16 v[24:27], v[84:87], v[108:111], v[20:23]
	v_mfma_f32_16x16x32_bf16 v[20:23], v[80:83], v[116:119], v[72:75]
	v_mfma_f32_16x16x32_bf16 v[16:19], v[84:87], v[116:119], v[76:79]
	v_mfma_f32_16x16x32_bf16 v[12:15], v[80:83], v[124:127], v[64:67]
	v_mfma_f32_16x16x32_bf16 v[4:7], v[84:87], v[124:127], v[68:71]
	s_setprio 0
	v_cmp_gt_u32_e32 vcc, s85, v135
	s_barrier
	s_and_saveexec_b64 s[64:65], vcc
	s_cbranch_execz .LBB0_277
	s_barrier

.LBB0_561:
	ds_read_b128 v[162:165], v161
	ds_read_b128 v[166:169], v161 offset:1024
	ds_read_b128 v[170:173], v161 offset:2048
	ds_read_b128 v[174:177], v161 offset:3072
	ds_read_b128 v[178:181], v152
	ds_read_b128 v[182:185], v152 offset:1024
	ds_read_b128 v[186:189], v151
	ds_read_b128 v[190:193], v151 offset:1024
	ds_read_b128 v[194:197], v150
	ds_read_b128 v[198:201], v150 offset:1024
	ds_read_b128 v[202:205], v149
	ds_read_b128 v[206:209], v149 offset:1024
	s_waitcnt lgkmcnt(8)
	s_waitcnt vmcnt(10)
	s_barrier
	s_waitcnt lgkmcnt(0)
	s_waitcnt lgkmcnt(0)
	v_mfma_f32_16x16x32_bf16 v[124:127], v[162:165], v[178:181], v[124:127]
	v_mfma_f32_16x16x32_bf16 v[120:123], v[170:173], v[178:181], v[120:123]
	v_mfma_f32_16x16x32_bf16 v[116:119], v[162:165], v[186:189], v[116:119]
	v_mfma_f32_16x16x32_bf16 v[112:115], v[170:173], v[186:189], v[112:115]
	v_mfma_f32_16x16x32_bf16 v[108:111], v[162:165], v[194:197], v[108:111]
	v_mfma_f32_16x16x32_bf16 v[104:107], v[170:173], v[194:197], v[104:107]
	v_mfma_f32_16x16x32_bf16 v[100:103], v[162:165], v[202:205], v[100:103]
	v_mfma_f32_16x16x32_bf16 v[96:99], v[170:173], v[202:205], v[96:99]
	v_mfma_f32_16x16x32_bf16 v[124:127], v[166:169], v[182:185], v[124:127]
	v_mfma_f32_16x16x32_bf16 v[120:123], v[174:177], v[182:185], v[120:123]
	v_mfma_f32_16x16x32_bf16 v[116:119], v[166:169], v[190:193], v[116:119]
	v_mfma_f32_16x16x32_bf16 v[112:115], v[174:177], v[190:193], v[112:115]
	v_mfma_f32_16x16x32_bf16 v[108:111], v[166:169], v[198:201], v[108:111]
	v_mfma_f32_16x16x32_bf16 v[104:107], v[174:177], v[198:201], v[104:107]
	v_mfma_f32_16x16x32_bf16 v[100:103], v[166:169], v[206:209], v[100:103]
	v_mfma_f32_16x16x32_bf16 v[96:99], v[174:177], v[206:209], v[96:99]
	s_barrier
	s_add_i32 s36, s98, 0x10000
	v_lshl_add_u64 v[226:227], v[130:131], 0, s[26:27]
	s_mov_b32 m0, s36
	s_add_i32 s36, s98, 0x12000
	ds_read_b128 v[210:213], v158
	ds_read_b128 v[214:217], v158 offset:1024
	ds_read_b128 v[218:221], v158 offset:2048
	ds_read_b128 v[222:225], v158 offset:3072
	global_load_lds_dwordx4 v[226:227], off
	v_lshl_add_u64 v[226:227], v[130:131], 0, s[28:29]
	s_mov_b32 m0, s36
	s_add_i32 s68, s68, 2
	global_load_lds_dwordx4 v[226:227], off
	s_mov_b32 s36, s98
	v_lshl_add_u64 v[226:227], v[132:133], 0, s[30:31]
	s_mov_b32 m0, s36
	s_add_i32 s36, s98, 0x2000
	global_load_lds_dwordx4 v[226:227], off nt
	v_lshl_add_u64 v[226:227], v[132:133], 0, s[34:35]
	s_mov_b32 m0, s36
	s_nop 0
	global_load_lds_dwordx4 v[226:227], off nt
	s_waitcnt vmcnt(12)
	s_barrier
	s_waitcnt lgkmcnt(0)
	s_waitcnt lgkmcnt(0)
	v_mfma_f32_16x16x32_bf16 v[92:95], v[210:213], v[178:181], v[92:95]
	v_mfma_f32_16x16x32_bf16 v[88:91], v[218:221], v[178:181], v[88:91]
	v_mfma_f32_16x16x32_bf16 v[84:87], v[210:213], v[186:189], v[84:87]
	v_mfma_f32_16x16x32_bf16 v[80:83], v[218:221], v[186:189], v[80:83]
	v_mfma_f32_16x16x32_bf16 v[76:79], v[210:213], v[194:197], v[76:79]
	v_mfma_f32_16x16x32_bf16 v[72:75], v[218:221], v[194:197], v[72:75]
	v_mfma_f32_16x16x32_bf16 v[68:71], v[210:213], v[202:205], v[68:71]
	v_mfma_f32_16x16x32_bf16 v[64:67], v[218:221], v[202:205], v[64:67]
	v_mfma_f32_16x16x32_bf16 v[92:95], v[214:217], v[182:185], v[92:95]
	v_mfma_f32_16x16x32_bf16 v[88:91], v[222:225], v[182:185], v[88:91]
	v_mfma_f32_16x16x32_bf16 v[84:87], v[214:217], v[190:193], v[84:87]
	v_mfma_f32_16x16x32_bf16 v[80:83], v[222:225], v[190:193], v[80:83]
	v_mfma_f32_16x16x32_bf16 v[76:79], v[214:217], v[198:201], v[76:79]
	v_mfma_f32_16x16x32_bf16 v[72:75], v[222:225], v[198:201], v[72:75]
	v_mfma_f32_16x16x32_bf16 v[68:71], v[214:217], v[206:209], v[68:71]
	v_mfma_f32_16x16x32_bf16 v[64:67], v[222:225], v[206:209], v[64:67]
	s_barrier
	ds_read_b128 v[178:181], v152 offset:16384
	ds_read_b128 v[182:185], v152 offset:17408
	ds_read_b128 v[186:189], v151 offset:16384
	ds_read_b128 v[190:193], v151 offset:17408
	ds_read_b128 v[194:197], v150 offset:16384
	ds_read_b128 v[198:201], v150 offset:17408
	ds_read_b128 v[202:205], v149 offset:16384
	ds_read_b128 v[206:209], v149 offset:17408
	s_add_i32 s36, s98, 0x14000
	v_lshl_add_u64 v[226:227], v[130:131], 0, s[38:39]
	s_mov_b32 m0, s36
	s_add_i32 s36, s98, 0x16000
	global_load_lds_dwordx4 v[226:227], off
	v_lshl_add_u64 v[226:227], v[130:131], 0, s[44:45]
	s_mov_b32 m0, s36
	s_nop 0
	global_load_lds_dwordx4 v[226:227], off
	s_barrier
	s_waitcnt lgkmcnt(0)
	s_waitcnt lgkmcnt(0)
	v_mfma_f32_16x16x32_bf16 v[60:63], v[162:165], v[178:181], v[60:63]
	v_mfma_f32_16x16x32_bf16 v[56:59], v[170:173], v[178:181], v[56:59]
	v_mfma_f32_16x16x32_bf16 v[52:55], v[162:165], v[186:189], v[52:55]
	v_mfma_f32_16x16x32_bf16 v[48:51], v[170:173], v[186:189], v[48:51]
	v_mfma_f32_16x16x32_bf16 v[44:47], v[162:165], v[194:197], v[44:47]
	v_mfma_f32_16x16x32_bf16 v[40:43], v[170:173], v[194:197], v[40:43]
	v_mfma_f32_16x16x32_bf16 v[36:39], v[162:165], v[202:205], v[36:39]
	v_mfma_f32_16x16x32_bf16 v[32:35], v[170:173], v[202:205], v[32:35]
	v_mfma_f32_16x16x32_bf16 v[60:63], v[166:169], v[182:185], v[60:63]
	v_mfma_f32_16x16x32_bf16 v[56:59], v[174:177], v[182:185], v[56:59]
	v_mfma_f32_16x16x32_bf16 v[52:55], v[166:169], v[190:193], v[52:55]
	v_mfma_f32_16x16x32_bf16 v[48:51], v[174:177], v[190:193], v[48:51]
	v_mfma_f32_16x16x32_bf16 v[44:47], v[166:169], v[198:201], v[44:47]
	v_mfma_f32_16x16x32_bf16 v[40:43], v[174:177], v[198:201], v[40:43]
	v_mfma_f32_16x16x32_bf16 v[36:39], v[166:169], v[206:209], v[36:39]
	v_mfma_f32_16x16x32_bf16 v[32:35], v[174:177], v[206:209], v[32:35]
	s_barrier
	s_add_i32 s36, s98, 0x4000
	v_lshl_add_u64 v[164:165], v[132:133], 0, s[46:47]
	s_mov_b32 m0, s36
	s_add_i32 s36, s98, 0x6000
	global_load_lds_dwordx4 v[164:165], off nt
	v_lshl_add_u64 v[164:165], v[132:133], 0, s[50:51]
	s_mov_b32 m0, s36
	s_nop 0
	global_load_lds_dwordx4 v[164:165], off nt
	s_waitcnt vmcnt(12)
	s_barrier
	v_mfma_f32_16x16x32_bf16 v[28:31], v[210:213], v[178:181], v[28:31]
	v_mfma_f32_16x16x32_bf16 v[24:27], v[218:221], v[178:181], v[24:27]
	v_mfma_f32_16x16x32_bf16 v[20:23], v[210:213], v[186:189], v[20:23]
	v_mfma_f32_16x16x32_bf16 v[16:19], v[218:221], v[186:189], v[16:19]
	v_mfma_f32_16x16x32_bf16 v[12:15], v[210:213], v[194:197], v[12:15]
	v_mfma_f32_16x16x32_bf16 v[8:11], v[218:221], v[194:197], v[8:11]
	v_mfma_f32_16x16x32_bf16 v[4:7], v[210:213], v[202:205], v[4:7]
	v_mfma_f32_16x16x32_bf16 v[0:3], v[218:221], v[202:205], v[0:3]
	v_mfma_f32_16x16x32_bf16 v[28:31], v[214:217], v[182:185], v[28:31]
	v_mfma_f32_16x16x32_bf16 v[24:27], v[222:225], v[182:185], v[24:27]
	v_mfma_f32_16x16x32_bf16 v[20:23], v[214:217], v[190:193], v[20:23]
	v_mfma_f32_16x16x32_bf16 v[16:19], v[222:225], v[190:193], v[16:19]
	v_mfma_f32_16x16x32_bf16 v[12:15], v[214:217], v[198:201], v[12:15]
	v_mfma_f32_16x16x32_bf16 v[8:11], v[222:225], v[198:201], v[8:11]
	v_mfma_f32_16x16x32_bf16 v[4:7], v[214:217], v[206:209], v[4:7]
	v_mfma_f32_16x16x32_bf16 v[0:3], v[222:225], v[206:209], v[0:3]
	s_barrier
	ds_read_b128 v[162:165], v154
	ds_read_b128 v[166:169], v154 offset:1024
	ds_read_b128 v[170:173], v154 offset:2048
	ds_read_b128 v[174:177], v154 offset:3072
	ds_read_b128 v[178:181], v152 offset:32768
	ds_read_b128 v[182:185], v152 offset:33792
	ds_read_b128 v[186:189], v151 offset:32768
	ds_read_b128 v[190:193], v151 offset:33792
	ds_read_b128 v[194:197], v150 offset:32768
	ds_read_b128 v[198:201], v150 offset:33792
	ds_read_b128 v[202:205], v149 offset:32768
	ds_read_b128 v[206:209], v149 offset:33792
	s_waitcnt lgkmcnt(8)
	s_waitcnt vmcnt(10)
	s_barrier
	s_waitcnt lgkmcnt(0)
	s_waitcnt lgkmcnt(0)
	v_mfma_f32_16x16x32_bf16 v[124:127], v[162:165], v[178:181], v[124:127]
	v_mfma_f32_16x16x32_bf16 v[120:123], v[170:173], v[178:181], v[120:123]
	v_mfma_f32_16x16x32_bf16 v[116:119], v[162:165], v[186:189], v[116:119]
	v_mfma_f32_16x16x32_bf16 v[112:115], v[170:173], v[186:189], v[112:115]
	v_mfma_f32_16x16x32_bf16 v[108:111], v[162:165], v[194:197], v[108:111]
	v_mfma_f32_16x16x32_bf16 v[104:107], v[170:173], v[194:197], v[104:107]
	v_mfma_f32_16x16x32_bf16 v[100:103], v[162:165], v[202:205], v[100:103]
	v_mfma_f32_16x16x32_bf16 v[96:99], v[170:173], v[202:205], v[96:99]
	v_mfma_f32_16x16x32_bf16 v[124:127], v[166:169], v[182:185], v[124:127]
	v_mfma_f32_16x16x32_bf16 v[120:123], v[174:177], v[182:185], v[120:123]
	v_mfma_f32_16x16x32_bf16 v[116:119], v[166:169], v[190:193], v[116:119]
	v_mfma_f32_16x16x32_bf16 v[112:115], v[174:177], v[190:193], v[112:115]
	v_mfma_f32_16x16x32_bf16 v[108:111], v[166:169], v[198:201], v[108:111]
	v_mfma_f32_16x16x32_bf16 v[104:107], v[174:177], v[198:201], v[104:107]
	v_mfma_f32_16x16x32_bf16 v[100:103], v[166:169], v[206:209], v[100:103]
	v_mfma_f32_16x16x32_bf16 v[96:99], v[174:177], v[206:209], v[96:99]
	s_barrier
	s_add_i32 s36, s98, 0x18000
	v_lshl_add_u64 v[226:227], v[130:131], 0, s[56:57]
	s_mov_b32 m0, s36
	s_add_i32 s36, s98, 0x1a000
	ds_read_b128 v[210:213], v153
	ds_read_b128 v[214:217], v153 offset:1024
	ds_read_b128 v[218:221], v153 offset:2048
	ds_read_b128 v[222:225], v153 offset:3072
	global_load_lds_dwordx4 v[226:227], off
	v_lshl_add_u64 v[226:227], v[130:131], 0, s[58:59]
	s_mov_b32 m0, s36
	s_nop 0
	global_load_lds_dwordx4 v[226:227], off
	s_add_i32 s36, s98, 0x8000
	v_lshl_add_u64 v[226:227], v[132:133], 0, s[60:61]
	s_mov_b32 m0, s36
	s_add_i32 s36, s98, 0xa000
	global_load_lds_dwordx4 v[226:227], off nt
	s_mov_b32 m0, s36
	s_nop 0
	global_load_lds_dwordx4 v[132:133], off nt
	s_waitcnt vmcnt(12)
	s_barrier
	s_waitcnt lgkmcnt(0)
	s_waitcnt lgkmcnt(0)
	v_mfma_f32_16x16x32_bf16 v[92:95], v[210:213], v[178:181], v[92:95]
	v_mfma_f32_16x16x32_bf16 v[88:91], v[218:221], v[178:181], v[88:91]
	v_mfma_f32_16x16x32_bf16 v[84:87], v[210:213], v[186:189], v[84:87]
	v_mfma_f32_16x16x32_bf16 v[80:83], v[218:221], v[186:189], v[80:83]
	v_mfma_f32_16x16x32_bf16 v[76:79], v[210:213], v[194:197], v[76:79]
	v_mfma_f32_16x16x32_bf16 v[72:75], v[218:221], v[194:197], v[72:75]
	v_mfma_f32_16x16x32_bf16 v[68:71], v[210:213], v[202:205], v[68:71]
	v_mfma_f32_16x16x32_bf16 v[64:67], v[218:221], v[202:205], v[64:67]
	v_mfma_f32_16x16x32_bf16 v[92:95], v[214:217], v[182:185], v[92:95]
	v_mfma_f32_16x16x32_bf16 v[88:91], v[222:225], v[182:185], v[88:91]
	v_mfma_f32_16x16x32_bf16 v[84:87], v[214:217], v[190:193], v[84:87]
	v_mfma_f32_16x16x32_bf16 v[80:83], v[222:225], v[190:193], v[80:83]
	v_mfma_f32_16x16x32_bf16 v[76:79], v[214:217], v[198:201], v[76:79]
	v_mfma_f32_16x16x32_bf16 v[72:75], v[222:225], v[198:201], v[72:75]
	v_mfma_f32_16x16x32_bf16 v[68:71], v[214:217], v[206:209], v[68:71]
	v_mfma_f32_16x16x32_bf16 v[64:67], v[222:225], v[206:209], v[64:67]
	s_barrier
	ds_read_b128 v[178:181], v152 offset:49152
	ds_read_b128 v[182:185], v152 offset:50176
	ds_read_b128 v[186:189], v151 offset:49152
	ds_read_b128 v[190:193], v151 offset:50176
	ds_read_b128 v[194:197], v150 offset:49152
	ds_read_b128 v[198:201], v150 offset:50176
	ds_read_b128 v[202:205], v149 offset:49152
	ds_read_b128 v[206:209], v149 offset:50176
	s_add_i32 s36, s98, 0x1c000
	v_lshl_add_u64 v[226:227], v[130:131], 0, s[60:61]
	s_mov_b32 m0, s36
	s_add_i32 s36, s98, 0x1e000
	global_load_lds_dwordx4 v[226:227], off
	s_mov_b32 m0, s36
	s_nop 0
	global_load_lds_dwordx4 v[130:131], off
	s_barrier
	s_waitcnt lgkmcnt(0)
	s_waitcnt lgkmcnt(0)
	v_mfma_f32_16x16x32_bf16 v[60:63], v[162:165], v[178:181], v[60:63]
	v_mfma_f32_16x16x32_bf16 v[56:59], v[170:173], v[178:181], v[56:59]
	v_mfma_f32_16x16x32_bf16 v[52:55], v[162:165], v[186:189], v[52:55]
	v_mfma_f32_16x16x32_bf16 v[48:51], v[170:173], v[186:189], v[48:51]
	v_mfma_f32_16x16x32_bf16 v[44:47], v[162:165], v[194:197], v[44:47]
	v_mfma_f32_16x16x32_bf16 v[40:43], v[170:173], v[194:197], v[40:43]
	v_mfma_f32_16x16x32_bf16 v[36:39], v[162:165], v[202:205], v[36:39]
	v_mfma_f32_16x16x32_bf16 v[32:35], v[170:173], v[202:205], v[32:35]
	v_mfma_f32_16x16x32_bf16 v[60:63], v[166:169], v[182:185], v[60:63]
	v_mfma_f32_16x16x32_bf16 v[56:59], v[174:177], v[182:185], v[56:59]
	v_mfma_f32_16x16x32_bf16 v[52:55], v[166:169], v[190:193], v[52:55]
	v_mfma_f32_16x16x32_bf16 v[48:51], v[174:177], v[190:193], v[48:51]
	v_mfma_f32_16x16x32_bf16 v[44:47], v[166:169], v[198:201], v[44:47]
	v_mfma_f32_16x16x32_bf16 v[40:43], v[174:177], v[198:201], v[40:43]
	v_mfma_f32_16x16x32_bf16 v[36:39], v[166:169], v[206:209], v[36:39]
	v_mfma_f32_16x16x32_bf16 v[32:35], v[174:177], v[206:209], v[32:35]
	s_barrier
	v_lshl_add_u64 v[132:133], v[132:133], 0, s[64:65]
	s_add_i32 s36, s98, 0xc000
	v_lshl_add_u64 v[164:165], v[132:133], 0, s[22:23]
	s_mov_b32 m0, s36
	s_add_i32 s36, s98, 0xe000
	global_load_lds_dwordx4 v[164:165], off nt
	v_lshl_add_u64 v[164:165], v[132:133], 0, s[24:25]
	s_mov_b32 m0, s36
	s_nop 0
	global_load_lds_dwordx4 v[164:165], off nt
	s_waitcnt vmcnt(12)
	s_barrier
	v_mfma_f32_16x16x32_bf16 v[28:31], v[210:213], v[178:181], v[28:31]
	v_mfma_f32_16x16x32_bf16 v[24:27], v[218:221], v[178:181], v[24:27]
	v_mfma_f32_16x16x32_bf16 v[20:23], v[210:213], v[186:189], v[20:23]
	v_mfma_f32_16x16x32_bf16 v[16:19], v[218:221], v[186:189], v[16:19]
	v_mfma_f32_16x16x32_bf16 v[12:15], v[210:213], v[194:197], v[12:15]
	v_mfma_f32_16x16x32_bf16 v[8:11], v[218:221], v[194:197], v[8:11]
	v_mfma_f32_16x16x32_bf16 v[4:7], v[210:213], v[202:205], v[4:7]
	v_mfma_f32_16x16x32_bf16 v[0:3], v[218:221], v[202:205], v[0:3]
	v_mfma_f32_16x16x32_bf16 v[28:31], v[214:217], v[182:185], v[28:31]
	v_mfma_f32_16x16x32_bf16 v[24:27], v[222:225], v[182:185], v[24:27]
	v_mfma_f32_16x16x32_bf16 v[20:23], v[214:217], v[190:193], v[20:23]
	v_mfma_f32_16x16x32_bf16 v[16:19], v[222:225], v[190:193], v[16:19]
	v_mfma_f32_16x16x32_bf16 v[12:15], v[214:217], v[198:201], v[12:15]
	v_mfma_f32_16x16x32_bf16 v[8:11], v[222:225], v[198:201], v[8:11]
	v_mfma_f32_16x16x32_bf16 v[4:7], v[214:217], v[206:209], v[4:7]
	v_mfma_f32_16x16x32_bf16 v[0:3], v[222:225], v[206:209], v[0:3]
	v_lshl_add_u64 v[130:131], v[130:131], 0, s[62:63]
	s_cmp_lt_u32 s68, s67
	s_barrier
	s_cbranch_scc1 .LBB0_561
	s_lshl_b32 s36, s86, 5
	s_lshl_b32 s37, s86, 8
	s_and_b32 s36, s36, 0x1800
	s_and_b32 s37, s37, 0x700
	s_or_b32 s96, s37, s36
	s_lshl_b32 s36, s96, 6
	s_add_u32 s36, s70, s36
	s_addc_u32 s37, s71, 0
	s_add_i32 s20, s20, -1
	s_lshl_b64 s[68:69], s[20:21], 20
	v_add_u32_e32 v128, v156, v157
	s_add_u32 s68, s36, s68
	v_or_b32_e32 v128, v128, v155
	s_addc_u32 s69, s37, s69
	v_lshl_add_u64 v[156:157], s[68:69], 0, v[128:129]
	v_readfirstlane_b32 s20, v160
	v_lshl_add_u64 v[206:207], v[156:157], 0, s[4:5]
	s_mov_b32 m0, s20
	v_readfirstlane_b32 s20, v159
	ds_read_b128 v[130:133], v161
	ds_read_b128 v[162:165], v161 offset:1024
	ds_read_b128 v[166:169], v161 offset:2048
	ds_read_b128 v[170:173], v161 offset:3072
	ds_read_b128 v[174:177], v152
	ds_read_b128 v[178:181], v152 offset:1024
	ds_read_b128 v[182:185], v151
	ds_read_b128 v[186:189], v151 offset:1024
	ds_read_b128 v[190:193], v150
	ds_read_b128 v[194:197], v150 offset:1024
	ds_read_b128 v[198:201], v149
	ds_read_b128 v[202:205], v149 offset:1024
	global_load_lds_dwordx4 v[206:207], off
	v_lshl_add_u64 v[156:157], v[156:157], 0, s[6:7]
	s_mov_b32 m0, s20
	s_nop 0
	global_load_lds_dwordx4 v[156:157], off
	s_waitcnt vmcnt(10)
	s_barrier
	s_waitcnt lgkmcnt(0)
	s_setprio 1
	s_waitcnt lgkmcnt(0)
	v_mfma_f32_16x16x32_bf16 v[124:127], v[130:133], v[174:177], v[124:127]
	v_mfma_f32_16x16x32_bf16 v[120:123], v[166:169], v[174:177], v[120:123]
	v_mfma_f32_16x16x32_bf16 v[116:119], v[130:133], v[182:185], v[116:119]
	v_mfma_f32_16x16x32_bf16 v[112:115], v[166:169], v[182:185], v[112:115]
	v_mfma_f32_16x16x32_bf16 v[108:111], v[130:133], v[190:193], v[108:111]
	v_mfma_f32_16x16x32_bf16 v[104:107], v[166:169], v[190:193], v[104:107]
	v_mfma_f32_16x16x32_bf16 v[100:103], v[130:133], v[198:201], v[100:103]
	v_mfma_f32_16x16x32_bf16 v[96:99], v[166:169], v[198:201], v[96:99]
	v_mfma_f32_16x16x32_bf16 v[124:127], v[162:165], v[178:181], v[124:127]
	v_mfma_f32_16x16x32_bf16 v[120:123], v[170:173], v[178:181], v[120:123]
	v_mfma_f32_16x16x32_bf16 v[116:119], v[162:165], v[186:189], v[116:119]
	v_mfma_f32_16x16x32_bf16 v[112:115], v[170:173], v[186:189], v[112:115]
	v_mfma_f32_16x16x32_bf16 v[108:111], v[162:165], v[194:197], v[108:111]
	v_mfma_f32_16x16x32_bf16 v[104:107], v[170:173], v[194:197], v[104:107]
	v_mfma_f32_16x16x32_bf16 v[100:103], v[162:165], v[202:205], v[100:103]
	v_mfma_f32_16x16x32_bf16 v[96:99], v[170:173], v[202:205], v[96:99]
	s_setprio 0
	s_barrier
	ds_read_b128 v[206:209], v158
	ds_read_b128 v[210:213], v158 offset:1024
	ds_read_b128 v[214:217], v158 offset:2048
	ds_read_b128 v[156:159], v158 offset:3072
	s_barrier
	s_waitcnt lgkmcnt(0)
	s_setprio 1
	s_waitcnt lgkmcnt(0)
	v_mfma_f32_16x16x32_bf16 v[92:95], v[206:209], v[174:177], v[92:95]
	v_mfma_f32_16x16x32_bf16 v[88:91], v[214:217], v[174:177], v[88:91]
	v_mfma_f32_16x16x32_bf16 v[84:87], v[206:209], v[182:185], v[84:87]
	v_mfma_f32_16x16x32_bf16 v[80:83], v[214:217], v[182:185], v[80:83]
	v_mfma_f32_16x16x32_bf16 v[76:79], v[206:209], v[190:193], v[76:79]
	v_mfma_f32_16x16x32_bf16 v[72:75], v[214:217], v[190:193], v[72:75]
	v_mfma_f32_16x16x32_bf16 v[68:71], v[206:209], v[198:201], v[68:71]
	v_mfma_f32_16x16x32_bf16 v[64:67], v[214:217], v[198:201], v[64:67]
	v_mfma_f32_16x16x32_bf16 v[174:177], v[210:213], v[178:181], v[92:95]
	v_mfma_f32_16x16x32_bf16 v[178:181], v[156:159], v[178:181], v[88:91]
	v_mfma_f32_16x16x32_bf16 v[182:185], v[210:213], v[186:189], v[84:87]
	v_mfma_f32_16x16x32_bf16 v[186:189], v[156:159], v[186:189], v[80:83]
	v_mfma_f32_16x16x32_bf16 v[190:193], v[210:213], v[194:197], v[76:79]
	v_mfma_f32_16x16x32_bf16 v[194:197], v[156:159], v[194:197], v[72:75]
	v_mfma_f32_16x16x32_bf16 v[198:201], v[210:213], v[202:205], v[68:71]
	v_mfma_f32_16x16x32_bf16 v[202:205], v[156:159], v[202:205], v[64:67]
	s_setprio 0
	s_barrier
	s_nop 0
	ds_read_b128 v[64:67], v152 offset:16384
	ds_read_b128 v[68:71], v152 offset:17408
	ds_read_b128 v[72:75], v151 offset:16384
	ds_read_b128 v[76:79], v151 offset:17408
	ds_read_b128 v[80:83], v150 offset:16384
	ds_read_b128 v[84:87], v150 offset:17408
	ds_read_b128 v[88:91], v149 offset:16384
	ds_read_b128 v[92:95], v149 offset:17408
	s_waitcnt vmcnt(4)
	s_barrier
	s_waitcnt lgkmcnt(0)
	s_setprio 1
	s_waitcnt lgkmcnt(0)
	v_mfma_f32_16x16x32_bf16 v[60:63], v[130:133], v[64:67], v[60:63]
	v_mfma_f32_16x16x32_bf16 v[56:59], v[166:169], v[64:67], v[56:59]
	v_mfma_f32_16x16x32_bf16 v[52:55], v[130:133], v[72:75], v[52:55]
	v_mfma_f32_16x16x32_bf16 v[48:51], v[166:169], v[72:75], v[48:51]
	v_mfma_f32_16x16x32_bf16 v[218:221], v[130:133], v[80:83], v[44:47]
	v_mfma_f32_16x16x32_bf16 v[222:225], v[166:169], v[80:83], v[40:43]
	v_mfma_f32_16x16x32_bf16 v[130:133], v[130:133], v[88:91], v[36:39]
	v_mfma_f32_16x16x32_bf16 v[166:169], v[166:169], v[88:91], v[32:35]
	v_mfma_f32_16x16x32_bf16 v[32:35], v[162:165], v[68:71], v[60:63]
	v_mfma_f32_16x16x32_bf16 v[36:39], v[170:173], v[68:71], v[56:59]
	v_mfma_f32_16x16x32_bf16 v[40:43], v[162:165], v[76:79], v[52:55]
	v_mfma_f32_16x16x32_bf16 v[44:47], v[170:173], v[76:79], v[48:51]
	v_mfma_f32_16x16x32_bf16 v[48:51], v[162:165], v[84:87], v[218:221]
	v_mfma_f32_16x16x32_bf16 v[52:55], v[170:173], v[84:87], v[222:225]
	v_mfma_f32_16x16x32_bf16 v[56:59], v[162:165], v[92:95], v[130:133]
	v_mfma_f32_16x16x32_bf16 v[60:63], v[170:173], v[92:95], v[166:169]
	s_setprio 0
	s_setprio 1
	v_mfma_f32_16x16x32_bf16 v[28:31], v[206:209], v[64:67], v[28:31]
	v_mfma_f32_16x16x32_bf16 v[24:27], v[214:217], v[64:67], v[24:27]
	v_mfma_f32_16x16x32_bf16 v[20:23], v[206:209], v[72:75], v[20:23]
	v_mfma_f32_16x16x32_bf16 v[64:67], v[214:217], v[72:75], v[16:19]
	v_mfma_f32_16x16x32_bf16 v[72:75], v[206:209], v[80:83], v[12:15]
	v_mfma_f32_16x16x32_bf16 v[8:11], v[214:217], v[80:83], v[8:11]
	v_mfma_f32_16x16x32_bf16 v[80:83], v[206:209], v[88:91], v[4:7]
	v_mfma_f32_16x16x32_bf16 v[0:3], v[214:217], v[88:91], v[0:3]
	v_mfma_f32_16x16x32_bf16 v[4:7], v[210:213], v[68:71], v[28:31]
	v_mfma_f32_16x16x32_bf16 v[12:15], v[156:159], v[68:71], v[24:27]
	v_mfma_f32_16x16x32_bf16 v[16:19], v[210:213], v[76:79], v[20:23]
	v_mfma_f32_16x16x32_bf16 v[20:23], v[156:159], v[76:79], v[64:67]
	v_mfma_f32_16x16x32_bf16 v[24:27], v[210:213], v[84:87], v[72:75]
	v_mfma_f32_16x16x32_bf16 v[28:31], v[156:159], v[84:87], v[8:11]
	v_mfma_f32_16x16x32_bf16 v[64:67], v[210:213], v[92:95], v[80:83]
	v_mfma_f32_16x16x32_bf16 v[68:71], v[156:159], v[92:95], v[0:3]
	s_setprio 0
	s_barrier
	ds_read_b128 v[8:11], v154
	ds_read_b128 v[0:3], v154 offset:1024
	ds_read_b128 v[76:79], v154 offset:2048
	ds_read_b128 v[72:75], v154 offset:3072
	ds_read_b128 v[130:133], v152 offset:32768
	ds_read_b128 v[154:157], v152 offset:33792
	ds_read_b128 v[158:161], v151 offset:32768
	ds_read_b128 v[162:165], v151 offset:33792
	ds_read_b128 v[166:169], v150 offset:32768
	ds_read_b128 v[170:173], v150 offset:33792
	ds_read_b128 v[206:209], v149 offset:32768
	ds_read_b128 v[210:213], v149 offset:33792
	s_waitcnt vmcnt(2)
	s_barrier
	s_waitcnt lgkmcnt(0)
	s_setprio 1
	s_waitcnt lgkmcnt(0)
	v_mfma_f32_16x16x32_bf16 v[80:83], v[8:11], v[130:133], v[124:127]
	v_mfma_f32_16x16x32_bf16 v[84:87], v[76:79], v[130:133], v[120:123]
	v_mfma_f32_16x16x32_bf16 v[88:91], v[8:11], v[158:161], v[116:119]
	v_mfma_f32_16x16x32_bf16 v[92:95], v[76:79], v[158:161], v[112:115]
	v_mfma_f32_16x16x32_bf16 v[108:111], v[8:11], v[166:169], v[108:111]
	v_mfma_f32_16x16x32_bf16 v[104:107], v[76:79], v[166:169], v[104:107]
	v_mfma_f32_16x16x32_bf16 v[100:103], v[8:11], v[206:209], v[100:103]
	v_mfma_f32_16x16x32_bf16 v[96:99], v[76:79], v[206:209], v[96:99]
	v_mfma_f32_16x16x32_bf16 v[112:115], v[0:3], v[154:157], v[80:83]
	v_mfma_f32_16x16x32_bf16 v[116:119], v[72:75], v[154:157], v[84:87]
	v_mfma_f32_16x16x32_bf16 v[120:123], v[0:3], v[162:165], v[88:91]
	v_mfma_f32_16x16x32_bf16 v[124:127], v[72:75], v[162:165], v[92:95]
	v_mfma_f32_16x16x32_bf16 v[108:111], v[0:3], v[170:173], v[108:111]
	v_mfma_f32_16x16x32_bf16 v[104:107], v[72:75], v[170:173], v[104:107]
	v_mfma_f32_16x16x32_bf16 v[100:103], v[0:3], v[210:213], v[100:103]
	v_mfma_f32_16x16x32_bf16 v[96:99], v[72:75], v[210:213], v[96:99]
	s_setprio 0
	s_barrier
	ds_read_b128 v[88:91], v153
	ds_read_b128 v[80:83], v153 offset:1024
	ds_read_b128 v[92:95], v153 offset:2048
	ds_read_b128 v[84:87], v153 offset:3072
	s_waitcnt vmcnt(0)
	s_barrier
	s_waitcnt lgkmcnt(0)
	s_setprio 1
	s_waitcnt lgkmcnt(0)
	v_mfma_f32_16x16x32_bf16 v[174:177], v[88:91], v[130:133], v[174:177]
	v_mfma_f32_16x16x32_bf16 v[130:133], v[92:95], v[130:133], v[178:181]
	v_mfma_f32_16x16x32_bf16 v[178:181], v[88:91], v[158:161], v[182:185]
	v_mfma_f32_16x16x32_bf16 v[158:161], v[92:95], v[158:161], v[186:189]
	v_mfma_f32_16x16x32_bf16 v[182:185], v[88:91], v[166:169], v[190:193]
	v_mfma_f32_16x16x32_bf16 v[166:169], v[92:95], v[166:169], v[194:197]
	v_mfma_f32_16x16x32_bf16 v[186:189], v[88:91], v[206:209], v[198:201]
	v_mfma_f32_16x16x32_bf16 v[190:193], v[92:95], v[206:209], v[202:205]
	v_mfma_f32_16x16x32_bf16 v[174:177], v[80:83], v[154:157], v[174:177]
	v_mfma_f32_16x16x32_bf16 v[130:133], v[84:87], v[154:157], v[130:133]
	v_mfma_f32_16x16x32_bf16 v[154:157], v[80:83], v[162:165], v[178:181]
	v_mfma_f32_16x16x32_bf16 v[158:161], v[84:87], v[162:165], v[158:161]
	v_mfma_f32_16x16x32_bf16 v[162:165], v[80:83], v[170:173], v[182:185]
	v_mfma_f32_16x16x32_bf16 v[166:169], v[84:87], v[170:173], v[166:169]
	v_mfma_f32_16x16x32_bf16 v[170:173], v[80:83], v[210:213], v[186:189]
	v_mfma_f32_16x16x32_bf16 v[178:181], v[84:87], v[210:213], v[190:193]
	s_setprio 0
	s_barrier
	v_mbcnt_lo_u32_b32 v128, -1, 0
	v_mbcnt_hi_u32_b32 v128, -1, v128
	v_cvt_pk_bf16_f32 v112, v112, v113
	v_cvt_pk_bf16_f32 v113, v114, v115
	v_cvt_pk_bf16_f32 v114, v116, v117
	v_cvt_pk_bf16_f32 v115, v118, v119
	s_lshl_b32 s89, s66, 9
	v_add_u32_e32 v153, s74, v128
	v_ashrrev_i32_e32 v182, 6, v153
	v_and_b32_e32 v183, 15, v128
	v_and_b32_e32 v184, 48, v128
	v_mul_lo_u32 v185, v182, s79
	v_bfe_u32 v186, v128, 3, 3
	v_lshlrev_b32_e32 v128, 4, v128
	v_add_u32_e32 v185, 0x20000, v185
	v_lshrrev_b32_e32 v153, 2, v153
	v_and_b32_e32 v128, 0x70, v128
	v_mul_u32_u24_e32 v183, 0x90, v183
	v_and_b32_e32 v153, 64, v153
	v_add3_u32 v183, v185, v183, v184
	v_or_b32_e32 v184, v185, v128
	v_or3_b32 v153, s96, v153, v186
	v_mad_u32_u24 v184, v186, s81, v184
	ds_write_b128 v183, v[112:115]
	v_cvt_pk_bf16_f32 v112, v174, v175
	v_cvt_pk_bf16_f32 v113, v176, v177
	v_cvt_pk_bf16_f32 v114, v130, v131
	v_cvt_pk_bf16_f32 v115, v132, v133
	ds_write_b128 v183, v[112:115] offset:64
	v_lshlrev_b32_e32 v182, 7, v182
	ds_read_b128 v[112:115], v184
	v_lshlrev_b32_e32 v116, 12, v153
	v_and_or_b32 v116, v182, s82, v116
	v_or3_b32 v128, v116, s89, v128
	ds_read_b128 v[116:119], v184 offset:1152
	v_lshl_add_u64 v[130:131], s[0:1], 0, v[128:129]
	s_mov_b32 s20, 0x8000
	s_waitcnt lgkmcnt(0)
	global_store_dwordx4 v128, v[112:115], s[0:1]
	v_cvt_pk_bf16_f32 v108, v108, v109
	v_cvt_pk_bf16_f32 v109, v110, v111
	v_cvt_pk_bf16_f32 v110, v104, v105
	v_cvt_pk_bf16_f32 v111, v106, v107
	v_cvt_pk_bf16_f32 v104, v162, v163
	s_nop 1
	v_add_co_u32_e32 v112, vcc, s20, v130
	v_cvt_pk_bf16_f32 v114, v124, v125
	v_cvt_pk_bf16_f32 v115, v126, v127
	v_cvt_pk_bf16_f32 v105, v164, v165
	v_cvt_pk_bf16_f32 v106, v166, v167
	s_nop 1
	v_addc_co_u32_e32 v113, vcc, 0, v131, vcc
	global_store_dwordx4 v[112:113], v[116:119], off
	v_cvt_pk_bf16_f32 v112, v120, v121
	v_cvt_pk_bf16_f32 v113, v122, v123
	ds_write_b128 v183, v[112:115]
	v_cvt_pk_bf16_f32 v112, v154, v155
	v_cvt_pk_bf16_f32 v113, v156, v157
	v_cvt_pk_bf16_f32 v114, v158, v159
	v_cvt_pk_bf16_f32 v115, v160, v161
	ds_write_b128 v183, v[112:115] offset:64
	ds_read_b128 v[112:115], v184
	ds_read_b128 v[116:119], v184 offset:1152
	v_add_co_u32_e32 v120, vcc, s76, v130
	ds_write_b128 v183, v[108:111]
	v_cvt_pk_bf16_f32 v107, v168, v169
	ds_write_b128 v183, v[104:107] offset:64
	v_addc_co_u32_e32 v121, vcc, 0, v131, vcc
	ds_read_b128 v[104:107], v184
	ds_read_b128 v[108:111], v184 offset:1152
	s_waitcnt lgkmcnt(0)
	global_store_dwordx4 v[120:121], v[112:115], off
	v_cvt_pk_bf16_f32 v100, v100, v101
	v_cvt_pk_bf16_f32 v101, v102, v103
	v_cvt_pk_bf16_f32 v102, v96, v97
	v_cvt_pk_bf16_f32 v103, v98, v99
	ds_write_b128 v183, v[100:103]
	s_nop 0
	v_add_co_u32_e32 v112, vcc, s77, v130
	v_cvt_pk_bf16_f32 v96, v170, v171
	v_cvt_pk_bf16_f32 v97, v172, v173
	v_cvt_pk_bf16_f32 v98, v178, v179
	v_cvt_pk_bf16_f32 v99, v180, v181
	s_nop 1
	v_addc_co_u32_e32 v113, vcc, 0, v131, vcc
	global_store_dwordx4 v[112:113], v[116:119], off
	v_add_co_u32_e32 v112, vcc, s80, v130
	ds_write_b128 v183, v[96:99] offset:64
	s_nop 0
	v_addc_co_u32_e32 v113, vcc, 0, v131, vcc
	ds_read_b128 v[96:99], v184
	ds_read_b128 v[100:103], v184 offset:1152
	global_store_dwordx4 v[112:113], v[104:107], off
	s_nop 1
	v_add_co_u32_e32 v104, vcc, s83, v130
	s_nop 1
	v_addc_co_u32_e32 v105, vcc, 0, v131, vcc
	global_store_dwordx4 v[104:105], v[108:111], off
	v_add_co_u32_e32 v104, vcc, s85, v130
	s_nop 1
	v_addc_co_u32_e32 v105, vcc, 0, v131, vcc
	s_waitcnt lgkmcnt(0)
	global_store_dwordx4 v[104:105], v[96:99], off
	s_nop 1
	v_add_co_u32_e32 v96, vcc, s87, v130
	s_nop 1
	v_addc_co_u32_e32 v97, vcc, 0, v131, vcc
	global_store_dwordx4 v[96:97], v[100:103], off
	ds_read_b128 v[96:99], v152 offset:49152
	ds_read_b128 v[100:103], v152 offset:50176
	ds_read_b128 v[104:107], v151 offset:49152
	ds_read_b128 v[108:111], v151 offset:50176
	ds_read_b128 v[112:115], v150 offset:49152
	ds_read_b128 v[116:119], v150 offset:50176
	ds_read_b128 v[120:123], v149 offset:49152
	ds_read_b128 v[124:127], v149 offset:50176
	s_barrier
	s_waitcnt lgkmcnt(0)
	s_setprio 1
	s_waitcnt lgkmcnt(0)
	v_mfma_f32_16x16x32_bf16 v[32:35], v[8:11], v[96:99], v[32:35]
	v_mfma_f32_16x16x32_bf16 v[36:39], v[76:79], v[96:99], v[36:39]
	v_mfma_f32_16x16x32_bf16 v[40:43], v[8:11], v[104:107], v[40:43]
	v_mfma_f32_16x16x32_bf16 v[130:133], v[76:79], v[104:107], v[44:47]
	v_mfma_f32_16x16x32_bf16 v[150:153], v[8:11], v[112:115], v[48:51]
	v_mfma_f32_16x16x32_bf16 v[52:55], v[76:79], v[112:115], v[52:55]
	v_mfma_f32_16x16x32_bf16 v[8:11], v[8:11], v[120:123], v[56:59]
	v_mfma_f32_16x16x32_bf16 v[60:63], v[76:79], v[120:123], v[60:63]
	v_mfma_f32_16x16x32_bf16 v[56:59], v[0:3], v[100:103], v[32:35]
	v_mfma_f32_16x16x32_bf16 v[48:51], v[72:75], v[100:103], v[36:39]
	v_mfma_f32_16x16x32_bf16 v[44:47], v[0:3], v[108:111], v[40:43]
	v_mfma_f32_16x16x32_bf16 v[40:43], v[72:75], v[108:111], v[130:133]
	v_mfma_f32_16x16x32_bf16 v[36:39], v[0:3], v[116:119], v[150:153]
	v_mfma_f32_16x16x32_bf16 v[32:35], v[72:75], v[116:119], v[52:55]
	v_mfma_f32_16x16x32_bf16 v[8:11], v[0:3], v[124:127], v[8:11]
	v_mfma_f32_16x16x32_bf16 v[0:3], v[72:75], v[124:127], v[60:63]
	s_setprio 0
	s_setprio 1
	v_mfma_f32_16x16x32_bf16 v[4:7], v[88:91], v[96:99], v[4:7]
	v_mfma_f32_16x16x32_bf16 v[12:15], v[92:95], v[96:99], v[12:15]
	v_mfma_f32_16x16x32_bf16 v[16:19], v[88:91], v[104:107], v[16:19]
	v_mfma_f32_16x16x32_bf16 v[20:23], v[92:95], v[104:107], v[20:23]
	v_mfma_f32_16x16x32_bf16 v[72:75], v[88:91], v[112:115], v[24:27]
	v_mfma_f32_16x16x32_bf16 v[76:79], v[92:95], v[112:115], v[28:31]
	v_mfma_f32_16x16x32_bf16 v[64:67], v[88:91], v[120:123], v[64:67]
	v_mfma_f32_16x16x32_bf16 v[68:71], v[92:95], v[120:123], v[68:71]
	v_mfma_f32_16x16x32_bf16 v[60:63], v[80:83], v[100:103], v[4:7]
	v_mfma_f32_16x16x32_bf16 v[52:55], v[84:87], v[100:103], v[12:15]
	v_mfma_f32_16x16x32_bf16 v[28:31], v[80:83], v[108:111], v[16:19]
	v_mfma_f32_16x16x32_bf16 v[24:27], v[84:87], v[108:111], v[20:23]
	v_mfma_f32_16x16x32_bf16 v[20:23], v[80:83], v[116:119], v[72:75]
	v_mfma_f32_16x16x32_bf16 v[16:19], v[84:87], v[116:119], v[76:79]
	v_mfma_f32_16x16x32_bf16 v[12:15], v[80:83], v[124:127], v[64:67]
	v_mfma_f32_16x16x32_bf16 v[4:7], v[84:87], v[124:127], v[68:71]
	s_setprio 0
	v_cmp_gt_u32_e32 vcc, s88, v135
	s_barrier
	s_and_saveexec_b64 s[66:67], vcc
	s_cbranch_execz .LBB0_564
	s_barrier
